# mixers-A phase: half of the workgroups run their (bandwidth-bound) hgrn_sample units before their (compute-bound) gating units so the two overlap chip-wide
# speedup vs baseline: 1.0081x; 1.0081x over previous
.LBB0_221:
	s_mov_b32 s75, 0
	v_mov_b32_e32 v1, v176
	v_readlane_b32 s0, v253, 5
	s_nop 1
	v_add_u32_e32 v0, s0, v1
	s_mov_b32 s0, 0x80000
	v_cmp_gt_i32_e32 vcc, s0, v0
	s_and_saveexec_b64 s[0:1], vcc
	s_cbranch_execz .LBB0_254
	v_readlane_b32 s2, v254, 44
	v_mov_b32_e32 v72, v0
	s_nop 0
	v_lshl_add_u32 v3, v1, 3, s2
	s_mov_b64 s[2:3], 0
	s_branch .LBB0_224

.Lord_re265:
	v_readlane_b32 s0, v252, 49
	s_not_b32 s0, s0
	v_readlane_b32 s1, v252, 50
	s_add_i32 s16, s1, s0
	s_cmpk_lt_i32 s16, 0x200
	v_readlane_b32 s0, v252, 55
	s_cselect_b64 s[2:3], -1, 0
	s_lshl_b32 s4, s0, 8
	s_ashr_i32 s5, s4, 31
	s_lshl_b32 s17, s0, 2
	s_cmp_lg_u32 s75, 0
	s_cbranch_scc1 .Lord_cont
	v_readlane_b32 s6, v252, 49
	s_nop 3
	s_bitcmp1_b32 s6, 3
	s_cbranch_scc0 .Lord_cont
	s_mov_b32 s75, 1
	s_branch .Lord_hs_first
.Lord_cont:
	s_cmpk_gt_i32 s16, 0x1ff
	v_readlane_b32 s1, v252, 56
	s_cbranch_scc1 .LBB0_317
	v_readlane_b32 s0, v252, 50
	s_lshl_b32 s18, s16, 5
	s_lshl_b32 s19, s0, 5
	s_mov_b32 s46, s16
	s_branch .LBB0_268

.LBB0_320:
	s_or_b64 exec, exec, s[0:1]
	s_mov_b32 s19, s69
	s_cmp_eq_u32 s75, 2
	s_cbranch_scc1 .LBB0_327
.Lord_hs_first:
	s_andn2_b64 vcc, exec, s[2:3]
	s_waitcnt lgkmcnt(0)
	s_barrier
	s_cbranch_vccnz .LBB0_327
	v_readlane_b32 s0, v252, 55
	v_readlane_b32 s1, v252, 56
	s_lshl_b64 s[2:3], s[0:1], 9
	s_lshl_b64 s[4:5], s[0:1], 11
	s_branch .LBB0_323

.LBB0_327:
	s_cmp_eq_u32 s75, 1
	s_cbranch_scc0 .Lord_fin
	s_mov_b32 s75, 2
	s_branch .Lord_re265
